# v066 plus FFN-in loop with 4 barriers per iteration (halves run MFMA-LOAD and LOAD-MFMA between barriers), loop body duplicated per half
# baseline (speedup 1.0000x reference)
.LBB0_1555:
	s_andn2_b64 vcc, exec, s[0:1]
	s_cbranch_vccnz .LBB0_1818
	v_readlane_b32 s0, v255, 31
	v_readlane_b32 s1, v255, 32
	s_and_b64 s[0:1], s[0:1], exec
	s_cselect_b32 s24, 0x44, 64
	s_mul_i32 s68, s24, 44
	s_mov_b32 s25, s77
	s_mov_b32 s36, s76
	s_mov_b32 s4, s73
	s_cmp_ge_i32 s36, s68
	s_waitcnt vmcnt(0)
	v_mbcnt_lo_u32_b32 v16, -1, 0
	v_mbcnt_hi_u32_b32 v16, -1, v16
	s_cbranch_scc1 .LBB0_1572
	v_readlane_b32 s6, v255, 37
	s_mul_i32 s1, s6, 0x2c00000
	v_readlane_b32 s5, v254, 35
	s_mul_hi_u32 s0, s6, 0x2c00000
	s_add_u32 s37, s5, s1
	v_readlane_b32 s1, v254, 36
	s_addc_u32 s38, s1, s0
	s_lshl_b32 s41, s4, 10
	v_lshl_add_u32 v0, v16, 4, s41
	v_add_u32_e32 v2, 0x2000, v0
	v_ashrrev_i32_e32 v3, 31, v2
	v_lshrrev_b32_e32 v3, 22, v3
	v_add_u32_e32 v3, v2, v3
	v_ashrrev_i32_e32 v10, 10, v3
	v_mul_i32_i24_e32 v3, 0x400, v10
	v_sub_u32_e32 v2, v2, v3
	v_lshrrev_b32_e32 v3, 4, v2
	v_bitop3_b32 v2, v3, v2, 32 bitop3:0x6c
	v_ashrrev_i32_e32 v3, 31, v2
	v_lshrrev_b32_e32 v3, 26, v3
	v_add_u32_e32 v3, v2, v3
	v_ashrrev_i32_e32 v11, 6, v3
	v_lshlrev_b32_e32 v4, 3, v10
	v_and_b32_e32 v3, 0xffc0, v3
	v_and_b32_e32 v4, -16, v4
	v_sub_u32_e32 v2, v2, v3
	v_add_u32_e32 v4, v11, v4
	v_lshrrev_b16_e32 v3, 7, v2
	v_and_b32_e32 v5, 3, v11
	s_mov_b32 s0, 0xfffe0
	v_lshrrev_b32_e32 v6, 2, v4
	v_lshlrev_b32_e32 v7, 1, v4
	v_and_b32_e32 v3, 1, v3
	v_and_or_b32 v5, v4, s0, v5
	v_and_b32_e32 v6, 4, v6
	v_and_b32_e32 v7, 24, v7
	v_add_u16_e32 v2, v2, v3
	v_or3_b32 v5, v5, v6, v7
	v_lshlrev_b32_e32 v6, 5, v10
	v_ashrrev_i16_sdwa v2, v251, sext(v2) dst_sel:DWORD dst_unused:UNUSED_PAD src0_sel:DWORD src1_sel:BYTE_0
	v_and_b32_e32 v6, 32, v6
	v_bfe_i32 v12, v2, 0, 16
	v_add_lshl_u32 v2, v6, v12, 1
	v_lshl_add_u32 v130, v5, 12, v2
	v_lshl_add_u32 v132, v4, 12, v2
	v_ashrrev_i32_e32 v2, 31, v0
	v_lshrrev_b32_e32 v2, 22, v2
	v_add_u32_e32 v2, v0, v2
	v_ashrrev_i32_e32 v13, 10, v2
	v_mul_i32_i24_e32 v2, 0x400, v13
	v_sub_u32_e32 v0, v0, v2
	v_lshrrev_b32_e32 v2, 4, v0
	v_bitop3_b32 v0, v2, v0, 32 bitop3:0x6c
	v_ashrrev_i32_e32 v2, 31, v0
	v_lshrrev_b32_e32 v2, 26, v2
	v_add_u32_e32 v2, v0, v2
	v_lshlrev_b32_e32 v3, 3, v13
	v_ashrrev_i32_e32 v14, 6, v2
	v_and_b32_e32 v3, -16, v3
	v_add_u32_e32 v3, v14, v3
	v_and_b32_e32 v4, 3, v14
	s_ashr_i32 s42, s36, 31
	v_and_or_b32 v4, v3, s0, v4
	s_lshr_b32 s0, s42, 29
	s_add_i32 s0, s36, s0
	s_lshr_b32 s39, s68, 3
	s_ashr_i32 s1, s0, 3
	s_and_b32 s0, s0, -8
	s_or_b32 s40, s39, 1
	s_ashr_i32 s5, s4, 2
	s_sub_i32 s0, s36, s0
	s_cmp_lt_i32 s0, 0
	s_cselect_b32 s6, s40, s39
	s_mul_i32 s0, s0, s6
	s_add_i32 s0, s0, s1
	s_mul_hi_i32 s1, s0, 0x2e8ba2e9
	s_lshr_b32 s6, s1, 31
	s_ashr_i32 s1, s1, 6
	s_add_i32 s1, s1, s6
	v_readlane_b32 s7, v255, 38
	s_lshl_b32 s6, s1, 3
	s_sub_i32 s7, s24, s6
	s_min_i32 s7, s7, 8
	v_and_b32_e32 v2, 0xc0, v2
	s_abs_i32 s8, s7
	v_sub_u32_e32 v0, v0, v2
	v_cvt_f32_u32_e32 v2, s8
	s_sub_i32 s10, 0, s8
	s_mulk_i32 s1, 0x160
	s_sub_i32 s0, s0, s1
	v_rcp_iflag_f32_e32 v2, v2
	s_abs_i32 s9, s0
	s_xor_b32 s1, s0, s7
	s_ashr_i32 s1, s1, 31
	v_mul_f32_e32 v2, 0x4f7ffffe, v2
	v_cvt_u32_f32_e32 v2, v2
	v_lshrrev_b32_e32 v5, 2, v3
	v_lshlrev_b32_e32 v6, 1, v3
	v_and_b32_e32 v5, 4, v5
	v_readfirstlane_b32 s11, v2
	s_mul_i32 s10, s10, s11
	s_mul_hi_u32 s10, s11, s10
	s_add_i32 s11, s11, s10
	s_mul_hi_u32 s10, s9, s11
	s_mul_i32 s11, s10, s8
	s_sub_i32 s9, s9, s11
	s_add_i32 s11, s10, 1
	s_sub_i32 s12, s9, s8
	s_cmp_ge_u32 s9, s8
	s_cselect_b32 s10, s11, s10
	s_cselect_b32 s9, s12, s9
	s_add_i32 s11, s10, 1
	s_cmp_ge_u32 s9, s8
	s_cselect_b32 s8, s11, s10
	s_xor_b32 s8, s8, s1
	s_sub_i32 s16, s8, s1
	s_mul_i32 s1, s16, s7
	s_sub_i32 s0, s0, s1
	s_add_i32 s14, s6, s0
	v_and_b32_e32 v6, 24, v6
	s_ashr_i32 s15, s14, 31
	s_ashr_i32 s17, s16, 31
	v_or3_b32 v4, v4, v5, v6
	v_lshlrev_b32_e32 v5, 5, v13
	v_ashrrev_i16_sdwa v0, v251, sext(v0) dst_sel:DWORD dst_unused:UNUSED_PAD src0_sel:DWORD src1_sel:BYTE_0
	s_lshl_b64 s[0:1], s[14:15], 20
	s_lshl_b64 s[6:7], s[16:17], 20
	v_and_b32_e32 v5, 32, v5
	v_bfe_i32 v15, v0, 0, 16
	s_add_u32 s20, s37, s6
	v_add_lshl_u32 v5, v5, v15, 1
	s_addc_u32 s21, s38, s7
	s_add_i32 s17, s41, 0
	v_lshl_add_u32 v0, v4, 12, v5
	s_add_i32 m0, s17, 0x10000
	v_lshl_add_u32 v134, v3, 12, v5
	global_load_lds_dwordx4 v0, s[20:21]
	s_add_i32 m0, s17, 0x12000
	s_add_u32 s6, s20, 0x80000
	global_load_lds_dwordx4 v130, s[20:21]
	s_addc_u32 s7, s21, 0
	s_add_i32 m0, s17, 0x14000
	v_mov_b32_e32 v131, v1
	global_load_lds_dwordx4 v0, s[6:7]
	s_add_i32 m0, s17, 0x16000
	v_mov_b32_e32 v135, v1
	global_load_lds_dwordx4 v130, s[6:7]
	v_readlane_b32 s6, v253, 25
	v_readlane_b32 s7, v253, 26
	s_add_u32 s18, s6, s0
	s_addc_u32 s19, s7, s1
	s_add_i32 s43, s17, 0x2000
	s_mov_b32 m0, s17
	s_add_u32 s0, s18, 0x80000
	global_load_lds_dwordx4 v134, s[18:19]
	s_mov_b32 m0, s43
	s_addc_u32 s1, s19, 0
	s_add_i32 s44, s17, 0x4000
	global_load_lds_dwordx4 v132, s[18:19]
	s_mov_b32 m0, s44
	s_add_i32 s45, s17, 0x6000
	global_load_lds_dwordx4 v134, s[0:1]
	s_mov_b32 m0, s45
	v_mov_b32_e32 v133, v1
	global_load_lds_dwordx4 v132, s[0:1]
	s_cmp_eq_u32 s5, 1
	v_lshl_add_u64 v[8:9], s[20:21], 0, v[0:1]
	v_lshl_add_u64 v[6:7], s[20:21], 0, v[130:131]
	v_lshl_add_u64 v[2:3], s[18:19], 0, v[134:135]
	s_cselect_b64 s[0:1], -1, 0
	s_cmp_lg_u32 s5, 1
	v_lshl_add_u64 v[4:5], s[18:19], 0, v[132:133]
	s_cbranch_scc1 .LBB0_1559
.LBB0_1559:
	v_and_b32_e32 v17, 15, v16
	v_lshl_or_b32 v18, s5, 6, v17
	v_ashrrev_i32_e32 v20, 6, v16
	s_lshl_b32 s5, s5, 13
	v_lshl_add_u32 v22, v20, 10, s5
	s_lshl_b32 s5, s4, 5
	s_and_b32 s8, s5, 0x60
	s_add_i32 m0, s17, 0x18000
	v_lshl_add_u64 v[8:9], v[8:9], 0, s[2:3]
	s_lshr_b32 s5, s8, 3
	s_waitcnt vmcnt(2)
	s_barrier
	global_load_lds_dwordx4 v[8:9], off
	v_lshl_add_u64 v[6:7], v[6:7], 0, s[2:3]
	s_add_i32 m0, s17, 0x1a000
	s_add_i32 s46, s17, 0x8000
	s_add_i32 s47, s17, 0xa000
	global_load_lds_dwordx4 v[6:7], off
	v_lshl_add_u64 v[2:3], v[2:3], 0, s[2:3]
	s_mov_b32 m0, s46
	s_add_u32 s6, s20, 0x80080
	global_load_lds_dwordx4 v[2:3], off
	v_lshl_add_u64 v[2:3], v[4:5], 0, s[2:3]
	s_mov_b32 m0, s47
	s_addc_u32 s7, s21, 0
	global_load_lds_dwordx4 v[2:3], off
	s_add_i32 m0, s17, 0x1c000
	v_lshl_add_u64 v[2:3], s[6:7], 0, v[0:1]
	global_load_lds_dwordx4 v[2:3], off
	v_lshl_add_u64 v[2:3], s[6:7], 0, v[130:131]
	s_add_i32 m0, s17, 0x1e000
	v_ashrrev_i32_e32 v19, 1, v16
	global_load_lds_dwordx4 v[2:3], off
	v_and_b32_e32 v19, -8, v19
	v_or_b32_e32 v2, 16, v18
	v_add_u32_e32 v161, s8, v19
	v_ashrrev_i32_e32 v19, 31, v18
	v_ashrrev_i32_e32 v3, 31, v2
	v_lshlrev_b64 v[136:137], 7, v[18:19]
	v_lshlrev_b64 v[138:139], 7, v[2:3]
	v_or_b32_e32 v2, 32, v18
	s_mov_b64 s[6:7], 0x4000
	v_ashrrev_i32_e32 v3, 31, v2
	v_lshl_add_u64 v[144:145], v[136:137], 0, s[6:7]
	s_mov_b64 s[6:7], 0x4800
	v_lshlrev_b64 v[140:141], 7, v[2:3]
	v_or_b32_e32 v2, 48, v18
	v_lshl_add_u64 v[146:147], v[136:137], 0, s[6:7]
	s_mov_b64 s[6:7], 0x5000
	v_ashrrev_i32_e32 v3, 31, v2
	v_lshl_add_u64 v[148:149], v[136:137], 0, s[6:7]
	s_mov_b64 s[6:7], 0x5800
	v_lshlrev_b64 v[142:143], 7, v[2:3]
	v_lshl_add_u64 v[150:151], v[136:137], 0, s[6:7]
	v_and_b32_e32 v2, 56, v161
	v_readlane_b32 s6, v254, 48
	v_lshlrev_b32_e32 v2, 1, v2
	v_mov_b32_e32 v3, v1
	v_readlane_b32 s7, v254, 49
	v_and_b32_e32 v21, 48, v16
	v_lshlrev_b32_e32 v16, 2, v16
	v_lshl_add_u64 v[152:153], s[6:7], 0, v[2:3]
	v_lshlrev_b32_e32 v2, 15, v13
	v_and_b32_e32 v2, 0xffff0000, v2
	v_lshl_add_u32 v2, v14, 12, v2
	v_and_b32_e32 v3, 1, v13
	v_lshl_or_b32 v2, v3, 6, v2
	v_lshl_add_u32 v154, v15, 1, v2
	v_lshlrev_b32_e32 v2, 15, v10
	v_and_b32_e32 v2, 0xffff0000, v2
	v_lshl_or_b32 v17, v17, 6, v21
	v_and_b32_e32 v16, 32, v16
	s_waitcnt vmcnt(6)
	v_lshl_add_u32 v2, v11, 12, v2
	v_and_b32_e32 v3, 1, v10
	v_bitop3_b32 v21, v17, v22, v16 bitop3:0xde
	v_add_lshl_u32 v20, s5, v20, 10
	s_cmp_lt_u32 s4, 4
	v_lshl_or_b32 v2, v3, 6, v2
	v_bitop3_b32 v160, v17, v20, v16 bitop3:0xde
	s_cselect_b64 s[4:5], -1, 0
	s_ashr_i32 s48, s25, 31
	v_mov_b32_e32 v155, v1
	v_lshl_add_u32 v156, v12, 1, v2
	v_mov_b32_e32 v157, v1
	s_mov_b32 s49, 0
	v_add_u32_e32 v162, 0, v21
	s_barrier
	s_branch .LBB0_1562

.LBB0_1564:
	s_ashr_i32 s9, s8, 31
	s_lshl_b64 s[10:11], s[8:9], 20
	v_readlane_b32 s12, v253, 25
	v_readlane_b32 s13, v253, 26
	s_add_u32 s10, s12, s10
	s_addc_u32 s11, s13, s11
	s_and_b64 s[12:13], s[34:35], exec
	s_cselect_b32 s9, s11, s19
	s_cselect_b32 s15, s10, s18
	s_ashr_i32 s7, s6, 31
	s_lshl_b64 s[12:13], s[6:7], 20
	s_add_u32 s12, s37, s12
	s_addc_u32 s13, s38, s13
	s_and_b64 s[22:23], s[34:35], exec
	s_cselect_b32 s7, s13, s21
	s_cselect_b32 s50, s12, s20
	s_add_u32 s18, s18, 0x80080
	s_addc_u32 s19, s19, 0
	s_add_u32 s51, s20, 0x100
	s_addc_u32 s52, s21, 0
	s_mov_b32 s53, -2
	s_add_u32 s20, s18, 0xfff80080
	s_addc_u32 s21, s19, -1
	s_add_i32 s54, 0, 0x10000
	s_cmp_eq_u32 s53, 28
	s_cselect_b32 s23, s9, s21
	s_cselect_b32 s22, s15, s20
	v_add_u32_e32 v158, s54, v160
	s_cselect_b32 s21, s7, s52
	s_cselect_b32 s20, s50, s51
	s_add_i32 s56, 0, 0x14000
	ds_read_b128 v[164:167], v158
	ds_read_b128 v[168:171], v158 offset:1024
	ds_read_b128 v[172:175], v158 offset:2048
	ds_read_b128 v[176:179], v158 offset:3072
	v_add_u32_e32 v158, s56, v160
	ds_read_b128 v[180:183], v158
	ds_read_b128 v[184:187], v158 offset:1024
	ds_read_b128 v[188:191], v158 offset:2048
	ds_read_b128 v[192:195], v158 offset:3072
	v_lshl_add_u64 v[158:159], s[18:19], 0, v[154:155]
	s_add_i32 m0, s17, 0xc000
	ds_read_b128 v[196:199], v162
	ds_read_b128 v[200:203], v162 offset:1024
	ds_read_b128 v[204:207], v162 offset:2048
	ds_read_b128 v[220:223], v162 offset:3072
	ds_read_b128 v[224:227], v162 offset:4096
	ds_read_b128 v[228:231], v162 offset:5120
	ds_read_b128 v[232:235], v162 offset:6144
	ds_read_b128 v[236:239], v162 offset:7168
	global_load_lds_dwordx4 v[158:159], off
	v_lshl_add_u64 v[158:159], s[18:19], 0, v[156:157]
	s_add_i32 m0, s17, 0xe000
	s_nop 0
	global_load_lds_dwordx4 v[158:159], off
	s_waitcnt vmcnt(8)
	s_waitcnt lgkmcnt(0)
	s_setprio 1
	s_and_b64 vcc, exec, s[4:5]
	s_cbranch_vccz .Lpk4_0
	s_barrier
.Lpk4_0:
	v_mfma_f32_16x16x32_bf16 v[122:125], v[164:167], v[196:199], 0
	v_mfma_f32_16x16x32_bf16 v[114:117], v[172:175], v[196:199], 0
	v_mfma_f32_16x16x32_bf16 v[106:109], v[164:167], v[204:207], 0
	v_mfma_f32_16x16x32_bf16 v[98:101], v[172:175], v[204:207], 0
	v_mfma_f32_16x16x32_bf16 v[90:93], v[164:167], v[224:227], 0
	v_mfma_f32_16x16x32_bf16 v[82:85], v[172:175], v[224:227], 0
	v_mfma_f32_16x16x32_bf16 v[74:77], v[164:167], v[232:235], 0
	v_mfma_f32_16x16x32_bf16 v[66:69], v[172:175], v[232:235], 0
	v_mfma_f32_16x16x32_bf16 v[122:125], v[168:171], v[200:203], v[122:125]
	v_mfma_f32_16x16x32_bf16 v[114:117], v[176:179], v[200:203], v[114:117]
	v_mfma_f32_16x16x32_bf16 v[106:109], v[168:171], v[220:223], v[106:109]
	v_mfma_f32_16x16x32_bf16 v[98:101], v[176:179], v[220:223], v[98:101]
	v_mfma_f32_16x16x32_bf16 v[90:93], v[168:171], v[228:231], v[90:93]
	v_mfma_f32_16x16x32_bf16 v[82:85], v[176:179], v[228:231], v[82:85]
	v_mfma_f32_16x16x32_bf16 v[74:77], v[168:171], v[236:239], v[74:77]
	v_mfma_f32_16x16x32_bf16 v[66:69], v[176:179], v[236:239], v[66:69]
	s_setprio 0
	s_setprio 1
	v_mfma_f32_16x16x32_bf16 v[126:129], v[180:183], v[196:199], 0
	v_mfma_f32_16x16x32_bf16 v[118:121], v[188:191], v[196:199], 0
	v_mfma_f32_16x16x32_bf16 v[110:113], v[180:183], v[204:207], 0
	v_mfma_f32_16x16x32_bf16 v[102:105], v[188:191], v[204:207], 0
	v_mfma_f32_16x16x32_bf16 v[94:97], v[180:183], v[224:227], 0
	v_mfma_f32_16x16x32_bf16 v[86:89], v[188:191], v[224:227], 0
	v_mfma_f32_16x16x32_bf16 v[78:81], v[180:183], v[232:235], 0
	v_mfma_f32_16x16x32_bf16 v[70:73], v[188:191], v[232:235], 0
	v_mfma_f32_16x16x32_bf16 v[126:129], v[184:187], v[200:203], v[126:129]
	v_mfma_f32_16x16x32_bf16 v[118:121], v[192:195], v[200:203], v[118:121]
	v_mfma_f32_16x16x32_bf16 v[110:113], v[184:187], v[220:223], v[110:113]
	v_mfma_f32_16x16x32_bf16 v[102:105], v[192:195], v[220:223], v[102:105]
	v_mfma_f32_16x16x32_bf16 v[94:97], v[184:187], v[228:231], v[94:97]
	v_mfma_f32_16x16x32_bf16 v[86:89], v[192:195], v[228:231], v[86:89]
	v_mfma_f32_16x16x32_bf16 v[78:81], v[184:187], v[236:239], v[78:81]
	v_mfma_f32_16x16x32_bf16 v[70:73], v[192:195], v[236:239], v[70:73]
	s_and_b64 vcc, exec, s[4:5]
	s_cbranch_vccnz .Lpk4_1
	s_barrier
.Lpk4_1:
	s_setprio 0
	s_add_i32 s54, s54, s41
	v_lshl_add_u64 v[158:159], s[20:21], 0, v[0:1]
	s_mov_b32 m0, s54
	ds_read_b128 v[196:199], v162 offset:16384
	ds_read_b128 v[200:203], v162 offset:17408
	ds_read_b128 v[204:207], v162 offset:18432
	ds_read_b128 v[220:223], v162 offset:19456
	ds_read_b128 v[224:227], v162 offset:20480
	ds_read_b128 v[228:231], v162 offset:21504
	ds_read_b128 v[232:235], v162 offset:22528
	ds_read_b128 v[236:239], v162 offset:23552
	global_load_lds_dwordx4 v[158:159], off
	s_add_i32 m0, s54, 0x2000
	s_add_u32 s54, s20, 0x80000
	v_lshl_add_u64 v[208:209], s[20:21], 0, v[130:131]
	s_addc_u32 s55, s21, 0
	s_add_i32 s56, s56, s41
	global_load_lds_dwordx4 v[208:209], off
	v_lshl_add_u64 v[216:217], s[54:55], 0, v[0:1]
	s_mov_b32 m0, s56
	v_lshl_add_u64 v[244:245], s[22:23], 0, v[132:133]
	global_load_lds_dwordx4 v[216:217], off
	v_lshl_add_u64 v[216:217], s[54:55], 0, v[130:131]
	s_add_i32 m0, s56, 0x2000
	s_nop 0
	global_load_lds_dwordx4 v[216:217], off
	v_lshl_add_u64 v[216:217], s[22:23], 0, v[134:135]
	s_mov_b32 m0, s17
	s_nop 0
	global_load_lds_dwordx4 v[216:217], off
	s_mov_b32 m0, s43
	s_nop 0
	global_load_lds_dwordx4 v[244:245], off
	s_waitcnt vmcnt(8)
	s_waitcnt lgkmcnt(0)
	s_setprio 1
	s_and_b64 vcc, exec, s[4:5]
	s_cbranch_vccz .Lpk4_2
	s_barrier
.Lpk4_2:
	v_mfma_f32_16x16x32_bf16 v[58:61], v[164:167], v[196:199], 0
	v_mfma_f32_16x16x32_bf16 v[50:53], v[172:175], v[196:199], 0
	v_mfma_f32_16x16x32_bf16 v[42:45], v[164:167], v[204:207], 0
	v_mfma_f32_16x16x32_bf16 v[34:37], v[172:175], v[204:207], 0
	v_mfma_f32_16x16x32_bf16 v[26:29], v[164:167], v[224:227], 0
	v_mfma_f32_16x16x32_bf16 v[18:21], v[172:175], v[224:227], 0
	v_mfma_f32_16x16x32_bf16 v[10:13], v[164:167], v[232:235], 0
	v_mfma_f32_16x16x32_bf16 v[2:5], v[172:175], v[232:235], 0
	v_mfma_f32_16x16x32_bf16 v[58:61], v[168:171], v[200:203], v[58:61]
	v_mfma_f32_16x16x32_bf16 v[50:53], v[176:179], v[200:203], v[50:53]
	v_mfma_f32_16x16x32_bf16 v[42:45], v[168:171], v[220:223], v[42:45]
	v_mfma_f32_16x16x32_bf16 v[34:37], v[176:179], v[220:223], v[34:37]
	v_mfma_f32_16x16x32_bf16 v[26:29], v[168:171], v[228:231], v[26:29]
	v_mfma_f32_16x16x32_bf16 v[18:21], v[176:179], v[228:231], v[18:21]
	v_mfma_f32_16x16x32_bf16 v[10:13], v[168:171], v[236:239], v[10:13]
	v_mfma_f32_16x16x32_bf16 v[2:5], v[176:179], v[236:239], v[2:5]
	s_setprio 0
	s_setprio 1
	v_mfma_f32_16x16x32_bf16 v[62:65], v[180:183], v[196:199], 0
	v_mfma_f32_16x16x32_bf16 v[54:57], v[188:191], v[196:199], 0
	v_mfma_f32_16x16x32_bf16 v[46:49], v[180:183], v[204:207], 0
	v_mfma_f32_16x16x32_bf16 v[38:41], v[188:191], v[204:207], 0
	v_mfma_f32_16x16x32_bf16 v[30:33], v[180:183], v[224:227], 0
	v_mfma_f32_16x16x32_bf16 v[22:25], v[188:191], v[224:227], 0
	v_mfma_f32_16x16x32_bf16 v[14:17], v[180:183], v[232:235], 0
	v_mfma_f32_16x16x32_bf16 v[6:9], v[188:191], v[232:235], 0
	v_mfma_f32_16x16x32_bf16 v[62:65], v[184:187], v[200:203], v[62:65]
	v_mfma_f32_16x16x32_bf16 v[54:57], v[192:195], v[200:203], v[54:57]
	v_mfma_f32_16x16x32_bf16 v[46:49], v[184:187], v[220:223], v[46:49]
	v_mfma_f32_16x16x32_bf16 v[38:41], v[192:195], v[220:223], v[38:41]
	v_mfma_f32_16x16x32_bf16 v[30:33], v[184:187], v[228:231], v[30:33]
	v_mfma_f32_16x16x32_bf16 v[22:25], v[192:195], v[228:231], v[22:25]
	v_mfma_f32_16x16x32_bf16 v[14:17], v[184:187], v[236:239], v[14:17]
	v_mfma_f32_16x16x32_bf16 v[6:9], v[192:195], v[236:239], v[6:9]
	s_and_b64 vcc, exec, s[4:5]
	s_cbranch_vccnz .Lpk4_3
	s_barrier
.Lpk4_3:
	s_setprio 0
	s_add_i32 s54, 0, 0x18000
	v_add_u32_e32 v163, s54, v160
	s_add_i32 s55, 0, 0x1c000
	ds_read_b128 v[164:167], v163
	ds_read_b128 v[168:171], v163 offset:1024
	ds_read_b128 v[172:175], v163 offset:2048
	ds_read_b128 v[176:179], v163 offset:3072
	v_add_u32_e32 v163, s55, v160
	ds_read_b128 v[180:183], v163
	ds_read_b128 v[184:187], v163 offset:1024
	ds_read_b128 v[188:191], v163 offset:2048
	ds_read_b128 v[192:195], v163 offset:3072
	s_add_u32 s22, s22, 0x80000
	s_addc_u32 s23, s23, 0
	s_mov_b32 m0, s44
	v_lshl_add_u64 v[246:247], s[22:23], 0, v[134:135]
	ds_read_b128 v[196:199], v162 offset:32768
	ds_read_b128 v[200:203], v162 offset:33792
	ds_read_b128 v[204:207], v162 offset:34816
	ds_read_b128 v[220:223], v162 offset:35840
	ds_read_b128 v[224:227], v162 offset:36864
	ds_read_b128 v[228:231], v162 offset:37888
	ds_read_b128 v[232:235], v162 offset:38912
	ds_read_b128 v[236:239], v162 offset:39936
	global_load_lds_dwordx4 v[246:247], off
	v_lshl_add_u64 v[246:247], s[22:23], 0, v[132:133]
	s_mov_b32 m0, s45
	s_nop 0
	global_load_lds_dwordx4 v[246:247], off
	s_waitcnt vmcnt(8)
	s_waitcnt lgkmcnt(0)
	s_setprio 1
	s_and_b64 vcc, exec, s[4:5]
	s_cbranch_vccz .Lpk4_4
	s_barrier
.Lpk4_4:
	v_mfma_f32_16x16x32_bf16 v[122:125], v[164:167], v[196:199], v[122:125]
	v_mfma_f32_16x16x32_bf16 v[114:117], v[172:175], v[196:199], v[114:117]
	v_mfma_f32_16x16x32_bf16 v[106:109], v[164:167], v[204:207], v[106:109]
	v_mfma_f32_16x16x32_bf16 v[98:101], v[172:175], v[204:207], v[98:101]
	v_mfma_f32_16x16x32_bf16 v[90:93], v[164:167], v[224:227], v[90:93]
	v_mfma_f32_16x16x32_bf16 v[82:85], v[172:175], v[224:227], v[82:85]
	v_mfma_f32_16x16x32_bf16 v[74:77], v[164:167], v[232:235], v[74:77]
	v_mfma_f32_16x16x32_bf16 v[66:69], v[172:175], v[232:235], v[66:69]
	v_mfma_f32_16x16x32_bf16 v[122:125], v[168:171], v[200:203], v[122:125]
	v_mfma_f32_16x16x32_bf16 v[114:117], v[176:179], v[200:203], v[114:117]
	v_mfma_f32_16x16x32_bf16 v[106:109], v[168:171], v[220:223], v[106:109]
	v_mfma_f32_16x16x32_bf16 v[98:101], v[176:179], v[220:223], v[98:101]
	v_mfma_f32_16x16x32_bf16 v[90:93], v[168:171], v[228:231], v[90:93]
	v_mfma_f32_16x16x32_bf16 v[82:85], v[176:179], v[228:231], v[82:85]
	v_mfma_f32_16x16x32_bf16 v[74:77], v[168:171], v[236:239], v[74:77]
	v_mfma_f32_16x16x32_bf16 v[66:69], v[176:179], v[236:239], v[66:69]
	s_setprio 0
	s_setprio 1
	v_mfma_f32_16x16x32_bf16 v[126:129], v[180:183], v[196:199], v[126:129]
	v_mfma_f32_16x16x32_bf16 v[118:121], v[188:191], v[196:199], v[118:121]
	v_mfma_f32_16x16x32_bf16 v[110:113], v[180:183], v[204:207], v[110:113]
	v_mfma_f32_16x16x32_bf16 v[102:105], v[188:191], v[204:207], v[102:105]
	v_mfma_f32_16x16x32_bf16 v[94:97], v[180:183], v[224:227], v[94:97]
	v_mfma_f32_16x16x32_bf16 v[86:89], v[188:191], v[224:227], v[86:89]
	v_mfma_f32_16x16x32_bf16 v[78:81], v[180:183], v[232:235], v[78:81]
	v_mfma_f32_16x16x32_bf16 v[70:73], v[188:191], v[232:235], v[70:73]
	v_mfma_f32_16x16x32_bf16 v[126:129], v[184:187], v[200:203], v[126:129]
	v_mfma_f32_16x16x32_bf16 v[118:121], v[192:195], v[200:203], v[118:121]
	v_mfma_f32_16x16x32_bf16 v[110:113], v[184:187], v[220:223], v[110:113]
	v_mfma_f32_16x16x32_bf16 v[102:105], v[192:195], v[220:223], v[102:105]
	v_mfma_f32_16x16x32_bf16 v[94:97], v[184:187], v[228:231], v[94:97]
	v_mfma_f32_16x16x32_bf16 v[86:89], v[192:195], v[228:231], v[86:89]
	v_mfma_f32_16x16x32_bf16 v[78:81], v[184:187], v[236:239], v[78:81]
	v_mfma_f32_16x16x32_bf16 v[70:73], v[192:195], v[236:239], v[70:73]
	s_and_b64 vcc, exec, s[4:5]
	s_cbranch_vccnz .Lpk4_5
	s_barrier
.Lpk4_5:
	s_setprio 0
	s_add_i32 s22, s54, s41
	v_lshl_add_u64 v[158:159], v[158:159], 0, s[2:3]
	s_mov_b32 m0, s22
	ds_read_b128 v[196:199], v162 offset:49152
	ds_read_b128 v[200:203], v162 offset:50176
	ds_read_b128 v[204:207], v162 offset:51200
	ds_read_b128 v[220:223], v162 offset:52224
	ds_read_b128 v[224:227], v162 offset:53248
	ds_read_b128 v[228:231], v162 offset:54272
	ds_read_b128 v[232:235], v162 offset:55296
	ds_read_b128 v[236:239], v162 offset:56320
	global_load_lds_dwordx4 v[158:159], off
	s_add_i32 m0, s22, 0x2000
	s_add_u32 s20, s20, 0x80080
	v_lshl_add_u64 v[158:159], v[208:209], 0, s[2:3]
	s_addc_u32 s21, s21, 0
	s_add_i32 s22, s55, s41
	global_load_lds_dwordx4 v[158:159], off
	v_lshl_add_u64 v[158:159], s[20:21], 0, v[0:1]
	s_mov_b32 m0, s22
	s_nop 0
	global_load_lds_dwordx4 v[158:159], off
	v_lshl_add_u64 v[158:159], s[20:21], 0, v[130:131]
	s_add_i32 m0, s22, 0x2000
	s_nop 0
	global_load_lds_dwordx4 v[158:159], off
	v_lshl_add_u64 v[158:159], v[216:217], 0, s[2:3]
	s_mov_b32 m0, s46
	s_nop 0
	global_load_lds_dwordx4 v[158:159], off
	v_lshl_add_u64 v[158:159], v[244:245], 0, s[2:3]
	s_mov_b32 m0, s47
	s_nop 0
	global_load_lds_dwordx4 v[158:159], off
	s_waitcnt vmcnt(8)
	s_waitcnt lgkmcnt(0)
	s_setprio 1
	s_and_b64 vcc, exec, s[4:5]
	s_cbranch_vccz .Lpk4_6
	s_barrier
.Lpk4_6:
	v_mfma_f32_16x16x32_bf16 v[58:61], v[164:167], v[196:199], v[58:61]
	v_mfma_f32_16x16x32_bf16 v[50:53], v[172:175], v[196:199], v[50:53]
	v_mfma_f32_16x16x32_bf16 v[42:45], v[164:167], v[204:207], v[42:45]
	v_mfma_f32_16x16x32_bf16 v[34:37], v[172:175], v[204:207], v[34:37]
	v_mfma_f32_16x16x32_bf16 v[26:29], v[164:167], v[224:227], v[26:29]
	v_mfma_f32_16x16x32_bf16 v[18:21], v[172:175], v[224:227], v[18:21]
	v_mfma_f32_16x16x32_bf16 v[10:13], v[164:167], v[232:235], v[10:13]
	v_mfma_f32_16x16x32_bf16 v[2:5], v[172:175], v[232:235], v[2:5]
	v_mfma_f32_16x16x32_bf16 v[58:61], v[168:171], v[200:203], v[58:61]
	v_mfma_f32_16x16x32_bf16 v[50:53], v[176:179], v[200:203], v[50:53]
	v_mfma_f32_16x16x32_bf16 v[42:45], v[168:171], v[220:223], v[42:45]
	v_mfma_f32_16x16x32_bf16 v[34:37], v[176:179], v[220:223], v[34:37]
	v_mfma_f32_16x16x32_bf16 v[26:29], v[168:171], v[228:231], v[26:29]
	v_mfma_f32_16x16x32_bf16 v[18:21], v[176:179], v[228:231], v[18:21]
	v_mfma_f32_16x16x32_bf16 v[10:13], v[168:171], v[236:239], v[10:13]
	v_mfma_f32_16x16x32_bf16 v[2:5], v[176:179], v[236:239], v[2:5]
	s_setprio 0
	s_setprio 1
	v_mfma_f32_16x16x32_bf16 v[62:65], v[180:183], v[196:199], v[62:65]
	v_mfma_f32_16x16x32_bf16 v[54:57], v[188:191], v[196:199], v[54:57]
	v_mfma_f32_16x16x32_bf16 v[46:49], v[180:183], v[204:207], v[46:49]
	v_mfma_f32_16x16x32_bf16 v[38:41], v[188:191], v[204:207], v[38:41]
	v_mfma_f32_16x16x32_bf16 v[30:33], v[180:183], v[224:227], v[30:33]
	v_mfma_f32_16x16x32_bf16 v[22:25], v[188:191], v[224:227], v[22:25]
	v_mfma_f32_16x16x32_bf16 v[14:17], v[180:183], v[232:235], v[14:17]
	v_mfma_f32_16x16x32_bf16 v[6:9], v[188:191], v[232:235], v[6:9]
	v_mfma_f32_16x16x32_bf16 v[62:65], v[184:187], v[200:203], v[62:65]
	v_mfma_f32_16x16x32_bf16 v[54:57], v[192:195], v[200:203], v[54:57]
	v_mfma_f32_16x16x32_bf16 v[46:49], v[184:187], v[220:223], v[46:49]
	v_mfma_f32_16x16x32_bf16 v[38:41], v[192:195], v[220:223], v[38:41]
	v_mfma_f32_16x16x32_bf16 v[30:33], v[184:187], v[228:231], v[30:33]
	v_mfma_f32_16x16x32_bf16 v[22:25], v[192:195], v[228:231], v[22:25]
	v_mfma_f32_16x16x32_bf16 v[14:17], v[184:187], v[236:239], v[14:17]
	v_mfma_f32_16x16x32_bf16 v[6:9], v[192:195], v[236:239], v[6:9]
	s_and_b64 vcc, exec, s[4:5]
	s_cbranch_vccnz .Lpk4_7
	s_barrier
.Lpk4_7:
	s_setprio 0
	s_add_i32 s53, s53, 2
	s_add_u32 s18, s18, 0x100
	s_addc_u32 s19, s19, 0
	s_add_u32 s51, s51, 0x100
	s_addc_u32 s52, s52, 0
	s_cmp_gt_u32 s53, 29
	s_cbranch_scc1 .Lpeel_done_4

.Lh0_4:
	s_add_u32 s20, s18, 0xfff80080
	s_addc_u32 s21, s19, -1
	s_cmp_eq_u32 s53, 28
	s_cselect_b32 s23, s9, s21
	s_cselect_b32 s22, s15, s20
	s_cselect_b32 s21, s7, s52
	s_cselect_b32 s20, s50, s51
	s_add_i32 s54, 0, 0x10000
	s_add_i32 s56, 0, 0x14000
	v_add_u32_e32 v158, 0x10000, v160
	ds_read_b128 v[164:167], v158
	ds_read_b128 v[168:171], v158 offset:1024
	ds_read_b128 v[172:175], v158 offset:2048
	ds_read_b128 v[176:179], v158 offset:3072
	ds_read_b128 v[180:183], v158 offset:16384
	ds_read_b128 v[184:187], v158 offset:17408
	ds_read_b128 v[188:191], v158 offset:18432
	ds_read_b128 v[192:195], v158 offset:19456
	s_add_i32 m0, s17, 0xc000
	ds_read_b128 v[196:199], v162
	ds_read_b128 v[200:203], v162 offset:1024
	ds_read_b128 v[204:207], v162 offset:2048
	ds_read_b128 v[220:223], v162 offset:3072
	ds_read_b128 v[224:227], v162 offset:4096
	ds_read_b128 v[228:231], v162 offset:5120
	ds_read_b128 v[232:235], v162 offset:6144
	ds_read_b128 v[236:239], v162 offset:7168
	global_load_lds_dwordx4 v154, s[18:19]
	s_add_i32 m0, s17, 0xe000
	s_nop 0
	global_load_lds_dwordx4 v156, s[18:19]
	s_waitcnt vmcnt(8)
	s_waitcnt lgkmcnt(0)
	s_setprio 1
	s_barrier
	v_mfma_f32_16x16x32_bf16 v[122:125], v[164:167], v[196:199], v[122:125]
	v_mfma_f32_16x16x32_bf16 v[114:117], v[172:175], v[196:199], v[114:117]
	v_mfma_f32_16x16x32_bf16 v[106:109], v[164:167], v[204:207], v[106:109]
	v_mfma_f32_16x16x32_bf16 v[98:101], v[172:175], v[204:207], v[98:101]
	v_mfma_f32_16x16x32_bf16 v[90:93], v[164:167], v[224:227], v[90:93]
	v_mfma_f32_16x16x32_bf16 v[82:85], v[172:175], v[224:227], v[82:85]
	v_mfma_f32_16x16x32_bf16 v[74:77], v[164:167], v[232:235], v[74:77]
	v_mfma_f32_16x16x32_bf16 v[66:69], v[172:175], v[232:235], v[66:69]
	v_mfma_f32_16x16x32_bf16 v[122:125], v[168:171], v[200:203], v[122:125]
	v_mfma_f32_16x16x32_bf16 v[114:117], v[176:179], v[200:203], v[114:117]
	v_mfma_f32_16x16x32_bf16 v[106:109], v[168:171], v[220:223], v[106:109]
	v_mfma_f32_16x16x32_bf16 v[98:101], v[176:179], v[220:223], v[98:101]
	v_mfma_f32_16x16x32_bf16 v[90:93], v[168:171], v[228:231], v[90:93]
	v_mfma_f32_16x16x32_bf16 v[82:85], v[176:179], v[228:231], v[82:85]
	v_mfma_f32_16x16x32_bf16 v[74:77], v[168:171], v[236:239], v[74:77]
	v_mfma_f32_16x16x32_bf16 v[66:69], v[176:179], v[236:239], v[66:69]
	s_setprio 0
	s_setprio 1
	v_mfma_f32_16x16x32_bf16 v[126:129], v[180:183], v[196:199], v[126:129]
	v_mfma_f32_16x16x32_bf16 v[118:121], v[188:191], v[196:199], v[118:121]
	v_mfma_f32_16x16x32_bf16 v[110:113], v[180:183], v[204:207], v[110:113]
	v_mfma_f32_16x16x32_bf16 v[102:105], v[188:191], v[204:207], v[102:105]
	v_mfma_f32_16x16x32_bf16 v[94:97], v[180:183], v[224:227], v[94:97]
	v_mfma_f32_16x16x32_bf16 v[86:89], v[188:191], v[224:227], v[86:89]
	v_mfma_f32_16x16x32_bf16 v[78:81], v[180:183], v[232:235], v[78:81]
	v_mfma_f32_16x16x32_bf16 v[70:73], v[188:191], v[232:235], v[70:73]
	v_mfma_f32_16x16x32_bf16 v[126:129], v[184:187], v[200:203], v[126:129]
	v_mfma_f32_16x16x32_bf16 v[118:121], v[192:195], v[200:203], v[118:121]
	v_mfma_f32_16x16x32_bf16 v[110:113], v[184:187], v[220:223], v[110:113]
	v_mfma_f32_16x16x32_bf16 v[102:105], v[192:195], v[220:223], v[102:105]
	v_mfma_f32_16x16x32_bf16 v[94:97], v[184:187], v[228:231], v[94:97]
	v_mfma_f32_16x16x32_bf16 v[86:89], v[192:195], v[228:231], v[86:89]
	v_mfma_f32_16x16x32_bf16 v[78:81], v[184:187], v[236:239], v[78:81]
	v_mfma_f32_16x16x32_bf16 v[70:73], v[192:195], v[236:239], v[70:73]
	s_setprio 0
	s_add_i32 s54, s54, s41
	s_mov_b32 m0, s54
	ds_read_b128 v[196:199], v162 offset:16384
	ds_read_b128 v[200:203], v162 offset:17408
	ds_read_b128 v[204:207], v162 offset:18432
	ds_read_b128 v[220:223], v162 offset:19456
	ds_read_b128 v[224:227], v162 offset:20480
	ds_read_b128 v[228:231], v162 offset:21504
	ds_read_b128 v[232:235], v162 offset:22528
	ds_read_b128 v[236:239], v162 offset:23552
	global_load_lds_dwordx4 v0, s[20:21]
	s_add_i32 m0, s54, 0x2000
	s_add_u32 s54, s20, 0x80000
	s_addc_u32 s55, s21, 0
	s_add_i32 s56, s56, s41
	global_load_lds_dwordx4 v130, s[20:21]
	s_mov_b32 m0, s56
	s_nop 0
	global_load_lds_dwordx4 v0, s[54:55]
	s_add_i32 m0, s56, 0x2000
	s_nop 0
	global_load_lds_dwordx4 v130, s[54:55]
	s_mov_b32 m0, s17
	s_nop 0
	global_load_lds_dwordx4 v134, s[22:23]
	s_mov_b32 m0, s43
	s_nop 0
	global_load_lds_dwordx4 v132, s[22:23]
	s_waitcnt vmcnt(8)
	s_waitcnt lgkmcnt(0)
	s_setprio 1
	s_barrier
	v_mfma_f32_16x16x32_bf16 v[58:61], v[164:167], v[196:199], v[58:61]
	v_mfma_f32_16x16x32_bf16 v[50:53], v[172:175], v[196:199], v[50:53]
	v_mfma_f32_16x16x32_bf16 v[42:45], v[164:167], v[204:207], v[42:45]
	v_mfma_f32_16x16x32_bf16 v[34:37], v[172:175], v[204:207], v[34:37]
	v_mfma_f32_16x16x32_bf16 v[26:29], v[164:167], v[224:227], v[26:29]
	v_mfma_f32_16x16x32_bf16 v[18:21], v[172:175], v[224:227], v[18:21]
	v_mfma_f32_16x16x32_bf16 v[10:13], v[164:167], v[232:235], v[10:13]
	v_mfma_f32_16x16x32_bf16 v[2:5], v[172:175], v[232:235], v[2:5]
	v_mfma_f32_16x16x32_bf16 v[58:61], v[168:171], v[200:203], v[58:61]
	v_mfma_f32_16x16x32_bf16 v[50:53], v[176:179], v[200:203], v[50:53]
	v_mfma_f32_16x16x32_bf16 v[42:45], v[168:171], v[220:223], v[42:45]
	v_mfma_f32_16x16x32_bf16 v[34:37], v[176:179], v[220:223], v[34:37]
	v_mfma_f32_16x16x32_bf16 v[26:29], v[168:171], v[228:231], v[26:29]
	v_mfma_f32_16x16x32_bf16 v[18:21], v[176:179], v[228:231], v[18:21]
	v_mfma_f32_16x16x32_bf16 v[10:13], v[168:171], v[236:239], v[10:13]
	v_mfma_f32_16x16x32_bf16 v[2:5], v[176:179], v[236:239], v[2:5]
	s_setprio 0
	s_setprio 1
	v_mfma_f32_16x16x32_bf16 v[62:65], v[180:183], v[196:199], v[62:65]
	v_mfma_f32_16x16x32_bf16 v[54:57], v[188:191], v[196:199], v[54:57]
	v_mfma_f32_16x16x32_bf16 v[46:49], v[180:183], v[204:207], v[46:49]
	v_mfma_f32_16x16x32_bf16 v[38:41], v[188:191], v[204:207], v[38:41]
	v_mfma_f32_16x16x32_bf16 v[30:33], v[180:183], v[224:227], v[30:33]
	v_mfma_f32_16x16x32_bf16 v[22:25], v[188:191], v[224:227], v[22:25]
	v_mfma_f32_16x16x32_bf16 v[14:17], v[180:183], v[232:235], v[14:17]
	v_mfma_f32_16x16x32_bf16 v[6:9], v[188:191], v[232:235], v[6:9]
	v_mfma_f32_16x16x32_bf16 v[62:65], v[184:187], v[200:203], v[62:65]
	v_mfma_f32_16x16x32_bf16 v[54:57], v[192:195], v[200:203], v[54:57]
	v_mfma_f32_16x16x32_bf16 v[46:49], v[184:187], v[220:223], v[46:49]
	v_mfma_f32_16x16x32_bf16 v[38:41], v[192:195], v[220:223], v[38:41]
	v_mfma_f32_16x16x32_bf16 v[30:33], v[184:187], v[228:231], v[30:33]
	v_mfma_f32_16x16x32_bf16 v[22:25], v[192:195], v[228:231], v[22:25]
	v_mfma_f32_16x16x32_bf16 v[14:17], v[184:187], v[236:239], v[14:17]
	v_mfma_f32_16x16x32_bf16 v[6:9], v[192:195], v[236:239], v[6:9]
	s_setprio 0
	ds_read_b128 v[164:167], v158 offset:32768
	ds_read_b128 v[168:171], v158 offset:33792
	ds_read_b128 v[172:175], v158 offset:34816
	ds_read_b128 v[176:179], v158 offset:35840
	ds_read_b128 v[180:183], v158 offset:49152
	ds_read_b128 v[184:187], v158 offset:50176
	ds_read_b128 v[188:191], v158 offset:51200
	ds_read_b128 v[192:195], v158 offset:52224
	s_add_i32 s54, 0, 0x18000
	s_add_i32 s55, 0, 0x1c000
	s_add_u32 s22, s22, 0x80000
	s_addc_u32 s23, s23, 0
	s_mov_b32 m0, s44
	ds_read_b128 v[196:199], v162 offset:32768
	ds_read_b128 v[200:203], v162 offset:33792
	ds_read_b128 v[204:207], v162 offset:34816
	ds_read_b128 v[220:223], v162 offset:35840
	ds_read_b128 v[224:227], v162 offset:36864
	ds_read_b128 v[228:231], v162 offset:37888
	ds_read_b128 v[232:235], v162 offset:38912
	ds_read_b128 v[236:239], v162 offset:39936
	global_load_lds_dwordx4 v134, s[22:23]
	s_mov_b32 m0, s45
	s_nop 0
	global_load_lds_dwordx4 v132, s[22:23]
	s_waitcnt vmcnt(8)
	s_waitcnt lgkmcnt(0)
	s_setprio 1
	s_barrier
	v_mfma_f32_16x16x32_bf16 v[122:125], v[164:167], v[196:199], v[122:125]
	v_mfma_f32_16x16x32_bf16 v[114:117], v[172:175], v[196:199], v[114:117]
	v_mfma_f32_16x16x32_bf16 v[106:109], v[164:167], v[204:207], v[106:109]
	v_mfma_f32_16x16x32_bf16 v[98:101], v[172:175], v[204:207], v[98:101]
	v_mfma_f32_16x16x32_bf16 v[90:93], v[164:167], v[224:227], v[90:93]
	v_mfma_f32_16x16x32_bf16 v[82:85], v[172:175], v[224:227], v[82:85]
	v_mfma_f32_16x16x32_bf16 v[74:77], v[164:167], v[232:235], v[74:77]
	v_mfma_f32_16x16x32_bf16 v[66:69], v[172:175], v[232:235], v[66:69]
	v_mfma_f32_16x16x32_bf16 v[122:125], v[168:171], v[200:203], v[122:125]
	v_mfma_f32_16x16x32_bf16 v[114:117], v[176:179], v[200:203], v[114:117]
	v_mfma_f32_16x16x32_bf16 v[106:109], v[168:171], v[220:223], v[106:109]
	v_mfma_f32_16x16x32_bf16 v[98:101], v[176:179], v[220:223], v[98:101]
	v_mfma_f32_16x16x32_bf16 v[90:93], v[168:171], v[228:231], v[90:93]
	v_mfma_f32_16x16x32_bf16 v[82:85], v[176:179], v[228:231], v[82:85]
	v_mfma_f32_16x16x32_bf16 v[74:77], v[168:171], v[236:239], v[74:77]
	v_mfma_f32_16x16x32_bf16 v[66:69], v[176:179], v[236:239], v[66:69]
	s_setprio 0
	s_setprio 1
	v_mfma_f32_16x16x32_bf16 v[126:129], v[180:183], v[196:199], v[126:129]
	v_mfma_f32_16x16x32_bf16 v[118:121], v[188:191], v[196:199], v[118:121]
	v_mfma_f32_16x16x32_bf16 v[110:113], v[180:183], v[204:207], v[110:113]
	v_mfma_f32_16x16x32_bf16 v[102:105], v[188:191], v[204:207], v[102:105]
	v_mfma_f32_16x16x32_bf16 v[94:97], v[180:183], v[224:227], v[94:97]
	v_mfma_f32_16x16x32_bf16 v[86:89], v[188:191], v[224:227], v[86:89]
	v_mfma_f32_16x16x32_bf16 v[78:81], v[180:183], v[232:235], v[78:81]
	v_mfma_f32_16x16x32_bf16 v[70:73], v[188:191], v[232:235], v[70:73]
	v_mfma_f32_16x16x32_bf16 v[126:129], v[184:187], v[200:203], v[126:129]
	v_mfma_f32_16x16x32_bf16 v[118:121], v[192:195], v[200:203], v[118:121]
	v_mfma_f32_16x16x32_bf16 v[110:113], v[184:187], v[220:223], v[110:113]
	v_mfma_f32_16x16x32_bf16 v[102:105], v[192:195], v[220:223], v[102:105]
	v_mfma_f32_16x16x32_bf16 v[94:97], v[184:187], v[228:231], v[94:97]
	v_mfma_f32_16x16x32_bf16 v[86:89], v[192:195], v[228:231], v[86:89]
	v_mfma_f32_16x16x32_bf16 v[78:81], v[184:187], v[236:239], v[78:81]
	v_mfma_f32_16x16x32_bf16 v[70:73], v[192:195], v[236:239], v[70:73]
	s_setprio 0
	s_add_u32 vcc_lo, s22, 0xfff80080
	s_addc_u32 vcc_hi, s23, -1
	s_add_i32 s22, s54, s41
	s_add_i32 s56, s55, s41
	s_add_u32 s54, s20, 0x80
	s_addc_u32 s55, s21, 0
	s_add_u32 s20, s20, 0x80080
	s_addc_u32 s21, s21, 0
	s_mov_b32 m0, s22
	ds_read_b128 v[196:199], v162 offset:49152
	ds_read_b128 v[200:203], v162 offset:50176
	ds_read_b128 v[204:207], v162 offset:51200
	ds_read_b128 v[220:223], v162 offset:52224
	ds_read_b128 v[224:227], v162 offset:53248
	ds_read_b128 v[228:231], v162 offset:54272
	ds_read_b128 v[232:235], v162 offset:55296
	ds_read_b128 v[236:239], v162 offset:56320
	global_load_lds_dwordx4 v0, s[54:55]
	s_add_i32 m0, s22, 0x2000
	s_nop 0
	global_load_lds_dwordx4 v130, s[54:55]
	s_mov_b32 m0, s56
	s_nop 0
	global_load_lds_dwordx4 v0, s[20:21]
	s_add_i32 m0, s56, 0x2000
	s_nop 0
	global_load_lds_dwordx4 v130, s[20:21]
	s_mov_b32 m0, s46
	s_nop 0
	global_load_lds_dwordx4 v134, vcc
	s_mov_b32 m0, s47
	s_nop 0
	global_load_lds_dwordx4 v132, vcc
	s_waitcnt vmcnt(8)
	s_waitcnt lgkmcnt(0)
	s_setprio 1
	s_barrier
	v_mfma_f32_16x16x32_bf16 v[58:61], v[164:167], v[196:199], v[58:61]
	v_mfma_f32_16x16x32_bf16 v[50:53], v[172:175], v[196:199], v[50:53]
	v_mfma_f32_16x16x32_bf16 v[42:45], v[164:167], v[204:207], v[42:45]
	v_mfma_f32_16x16x32_bf16 v[34:37], v[172:175], v[204:207], v[34:37]
	v_mfma_f32_16x16x32_bf16 v[26:29], v[164:167], v[224:227], v[26:29]
	v_mfma_f32_16x16x32_bf16 v[18:21], v[172:175], v[224:227], v[18:21]
	v_mfma_f32_16x16x32_bf16 v[10:13], v[164:167], v[232:235], v[10:13]
	v_mfma_f32_16x16x32_bf16 v[2:5], v[172:175], v[232:235], v[2:5]
	v_mfma_f32_16x16x32_bf16 v[58:61], v[168:171], v[200:203], v[58:61]
	v_mfma_f32_16x16x32_bf16 v[50:53], v[176:179], v[200:203], v[50:53]
	v_mfma_f32_16x16x32_bf16 v[42:45], v[168:171], v[220:223], v[42:45]
	v_mfma_f32_16x16x32_bf16 v[34:37], v[176:179], v[220:223], v[34:37]
	v_mfma_f32_16x16x32_bf16 v[26:29], v[168:171], v[228:231], v[26:29]
	v_mfma_f32_16x16x32_bf16 v[18:21], v[176:179], v[228:231], v[18:21]
	v_mfma_f32_16x16x32_bf16 v[10:13], v[168:171], v[236:239], v[10:13]
	v_mfma_f32_16x16x32_bf16 v[2:5], v[176:179], v[236:239], v[2:5]
	s_setprio 0
	s_setprio 1
	v_mfma_f32_16x16x32_bf16 v[62:65], v[180:183], v[196:199], v[62:65]
	v_mfma_f32_16x16x32_bf16 v[54:57], v[188:191], v[196:199], v[54:57]
	v_mfma_f32_16x16x32_bf16 v[46:49], v[180:183], v[204:207], v[46:49]
	v_mfma_f32_16x16x32_bf16 v[38:41], v[188:191], v[204:207], v[38:41]
	v_mfma_f32_16x16x32_bf16 v[30:33], v[180:183], v[224:227], v[30:33]
	v_mfma_f32_16x16x32_bf16 v[22:25], v[188:191], v[224:227], v[22:25]
	v_mfma_f32_16x16x32_bf16 v[14:17], v[180:183], v[232:235], v[14:17]
	v_mfma_f32_16x16x32_bf16 v[6:9], v[188:191], v[232:235], v[6:9]
	v_mfma_f32_16x16x32_bf16 v[62:65], v[184:187], v[200:203], v[62:65]
	v_mfma_f32_16x16x32_bf16 v[54:57], v[192:195], v[200:203], v[54:57]
	v_mfma_f32_16x16x32_bf16 v[46:49], v[184:187], v[220:223], v[46:49]
	v_mfma_f32_16x16x32_bf16 v[38:41], v[192:195], v[220:223], v[38:41]
	v_mfma_f32_16x16x32_bf16 v[30:33], v[184:187], v[228:231], v[30:33]
	v_mfma_f32_16x16x32_bf16 v[22:25], v[192:195], v[228:231], v[22:25]
	v_mfma_f32_16x16x32_bf16 v[14:17], v[184:187], v[236:239], v[14:17]
	v_mfma_f32_16x16x32_bf16 v[6:9], v[192:195], v[236:239], v[6:9]
	s_setprio 0
	s_add_i32 s53, s53, 2
	s_add_u32 s18, s18, 0x100
	s_addc_u32 s19, s19, 0
	s_add_u32 s51, s51, 0x100
	s_addc_u32 s52, s52, 0
	s_cmp_gt_u32 s53, 29
	s_cbranch_scc0 .Lh0_4
	s_branch .Ldone_4
.Lh1_4:
	s_add_u32 s20, s18, 0xfff80080
	s_addc_u32 s21, s19, -1
	s_cmp_eq_u32 s53, 28
	s_cselect_b32 s23, s9, s21
	s_cselect_b32 s22, s15, s20
	s_cselect_b32 s21, s7, s52
	s_cselect_b32 s20, s50, s51
	s_add_i32 s54, 0, 0x10000
	s_add_i32 s56, 0, 0x14000
	v_add_u32_e32 v158, 0x10000, v160
	ds_read_b128 v[164:167], v158
	ds_read_b128 v[168:171], v158 offset:1024
	ds_read_b128 v[172:175], v158 offset:2048
	ds_read_b128 v[176:179], v158 offset:3072
	ds_read_b128 v[180:183], v158 offset:16384
	ds_read_b128 v[184:187], v158 offset:17408
	ds_read_b128 v[188:191], v158 offset:18432
	ds_read_b128 v[192:195], v158 offset:19456
	s_add_i32 m0, s17, 0xc000
	ds_read_b128 v[196:199], v162
	ds_read_b128 v[200:203], v162 offset:1024
	ds_read_b128 v[204:207], v162 offset:2048
	ds_read_b128 v[220:223], v162 offset:3072
	ds_read_b128 v[224:227], v162 offset:4096
	ds_read_b128 v[228:231], v162 offset:5120
	ds_read_b128 v[232:235], v162 offset:6144
	ds_read_b128 v[236:239], v162 offset:7168
	global_load_lds_dwordx4 v154, s[18:19]
	s_add_i32 m0, s17, 0xe000
	s_nop 0
	global_load_lds_dwordx4 v156, s[18:19]
	s_waitcnt vmcnt(8)
	s_waitcnt lgkmcnt(0)
	s_setprio 1
	v_mfma_f32_16x16x32_bf16 v[122:125], v[164:167], v[196:199], v[122:125]
	v_mfma_f32_16x16x32_bf16 v[114:117], v[172:175], v[196:199], v[114:117]
	v_mfma_f32_16x16x32_bf16 v[106:109], v[164:167], v[204:207], v[106:109]
	v_mfma_f32_16x16x32_bf16 v[98:101], v[172:175], v[204:207], v[98:101]
	v_mfma_f32_16x16x32_bf16 v[90:93], v[164:167], v[224:227], v[90:93]
	v_mfma_f32_16x16x32_bf16 v[82:85], v[172:175], v[224:227], v[82:85]
	v_mfma_f32_16x16x32_bf16 v[74:77], v[164:167], v[232:235], v[74:77]
	v_mfma_f32_16x16x32_bf16 v[66:69], v[172:175], v[232:235], v[66:69]
	v_mfma_f32_16x16x32_bf16 v[122:125], v[168:171], v[200:203], v[122:125]
	v_mfma_f32_16x16x32_bf16 v[114:117], v[176:179], v[200:203], v[114:117]
	v_mfma_f32_16x16x32_bf16 v[106:109], v[168:171], v[220:223], v[106:109]
	v_mfma_f32_16x16x32_bf16 v[98:101], v[176:179], v[220:223], v[98:101]
	v_mfma_f32_16x16x32_bf16 v[90:93], v[168:171], v[228:231], v[90:93]
	v_mfma_f32_16x16x32_bf16 v[82:85], v[176:179], v[228:231], v[82:85]
	v_mfma_f32_16x16x32_bf16 v[74:77], v[168:171], v[236:239], v[74:77]
	v_mfma_f32_16x16x32_bf16 v[66:69], v[176:179], v[236:239], v[66:69]
	s_setprio 0
	s_setprio 1
	v_mfma_f32_16x16x32_bf16 v[126:129], v[180:183], v[196:199], v[126:129]
	v_mfma_f32_16x16x32_bf16 v[118:121], v[188:191], v[196:199], v[118:121]
	v_mfma_f32_16x16x32_bf16 v[110:113], v[180:183], v[204:207], v[110:113]
	v_mfma_f32_16x16x32_bf16 v[102:105], v[188:191], v[204:207], v[102:105]
	v_mfma_f32_16x16x32_bf16 v[94:97], v[180:183], v[224:227], v[94:97]
	v_mfma_f32_16x16x32_bf16 v[86:89], v[188:191], v[224:227], v[86:89]
	v_mfma_f32_16x16x32_bf16 v[78:81], v[180:183], v[232:235], v[78:81]
	v_mfma_f32_16x16x32_bf16 v[70:73], v[188:191], v[232:235], v[70:73]
	v_mfma_f32_16x16x32_bf16 v[126:129], v[184:187], v[200:203], v[126:129]
	v_mfma_f32_16x16x32_bf16 v[118:121], v[192:195], v[200:203], v[118:121]
	v_mfma_f32_16x16x32_bf16 v[110:113], v[184:187], v[220:223], v[110:113]
	v_mfma_f32_16x16x32_bf16 v[102:105], v[192:195], v[220:223], v[102:105]
	v_mfma_f32_16x16x32_bf16 v[94:97], v[184:187], v[228:231], v[94:97]
	v_mfma_f32_16x16x32_bf16 v[86:89], v[192:195], v[228:231], v[86:89]
	v_mfma_f32_16x16x32_bf16 v[78:81], v[184:187], v[236:239], v[78:81]
	v_mfma_f32_16x16x32_bf16 v[70:73], v[192:195], v[236:239], v[70:73]
	s_barrier
	s_setprio 0
	s_add_i32 s54, s54, s41
	s_mov_b32 m0, s54
	ds_read_b128 v[196:199], v162 offset:16384
	ds_read_b128 v[200:203], v162 offset:17408
	ds_read_b128 v[204:207], v162 offset:18432
	ds_read_b128 v[220:223], v162 offset:19456
	ds_read_b128 v[224:227], v162 offset:20480
	ds_read_b128 v[228:231], v162 offset:21504
	ds_read_b128 v[232:235], v162 offset:22528
	ds_read_b128 v[236:239], v162 offset:23552
	global_load_lds_dwordx4 v0, s[20:21]
	s_add_i32 m0, s54, 0x2000
	s_add_u32 s54, s20, 0x80000
	s_addc_u32 s55, s21, 0
	s_add_i32 s56, s56, s41
	global_load_lds_dwordx4 v130, s[20:21]
	s_mov_b32 m0, s56
	s_nop 0
	global_load_lds_dwordx4 v0, s[54:55]
	s_add_i32 m0, s56, 0x2000
	s_nop 0
	global_load_lds_dwordx4 v130, s[54:55]
	s_mov_b32 m0, s17
	s_nop 0
	global_load_lds_dwordx4 v134, s[22:23]
	s_mov_b32 m0, s43
	s_nop 0
	global_load_lds_dwordx4 v132, s[22:23]
	s_waitcnt vmcnt(8)
	s_waitcnt lgkmcnt(0)
	s_setprio 1
	v_mfma_f32_16x16x32_bf16 v[58:61], v[164:167], v[196:199], v[58:61]
	v_mfma_f32_16x16x32_bf16 v[50:53], v[172:175], v[196:199], v[50:53]
	v_mfma_f32_16x16x32_bf16 v[42:45], v[164:167], v[204:207], v[42:45]
	v_mfma_f32_16x16x32_bf16 v[34:37], v[172:175], v[204:207], v[34:37]
	v_mfma_f32_16x16x32_bf16 v[26:29], v[164:167], v[224:227], v[26:29]
	v_mfma_f32_16x16x32_bf16 v[18:21], v[172:175], v[224:227], v[18:21]
	v_mfma_f32_16x16x32_bf16 v[10:13], v[164:167], v[232:235], v[10:13]
	v_mfma_f32_16x16x32_bf16 v[2:5], v[172:175], v[232:235], v[2:5]
	v_mfma_f32_16x16x32_bf16 v[58:61], v[168:171], v[200:203], v[58:61]
	v_mfma_f32_16x16x32_bf16 v[50:53], v[176:179], v[200:203], v[50:53]
	v_mfma_f32_16x16x32_bf16 v[42:45], v[168:171], v[220:223], v[42:45]
	v_mfma_f32_16x16x32_bf16 v[34:37], v[176:179], v[220:223], v[34:37]
	v_mfma_f32_16x16x32_bf16 v[26:29], v[168:171], v[228:231], v[26:29]
	v_mfma_f32_16x16x32_bf16 v[18:21], v[176:179], v[228:231], v[18:21]
	v_mfma_f32_16x16x32_bf16 v[10:13], v[168:171], v[236:239], v[10:13]
	v_mfma_f32_16x16x32_bf16 v[2:5], v[176:179], v[236:239], v[2:5]
	s_setprio 0
	s_setprio 1
	v_mfma_f32_16x16x32_bf16 v[62:65], v[180:183], v[196:199], v[62:65]
	v_mfma_f32_16x16x32_bf16 v[54:57], v[188:191], v[196:199], v[54:57]
	v_mfma_f32_16x16x32_bf16 v[46:49], v[180:183], v[204:207], v[46:49]
	v_mfma_f32_16x16x32_bf16 v[38:41], v[188:191], v[204:207], v[38:41]
	v_mfma_f32_16x16x32_bf16 v[30:33], v[180:183], v[224:227], v[30:33]
	v_mfma_f32_16x16x32_bf16 v[22:25], v[188:191], v[224:227], v[22:25]
	v_mfma_f32_16x16x32_bf16 v[14:17], v[180:183], v[232:235], v[14:17]
	v_mfma_f32_16x16x32_bf16 v[6:9], v[188:191], v[232:235], v[6:9]
	v_mfma_f32_16x16x32_bf16 v[62:65], v[184:187], v[200:203], v[62:65]
	v_mfma_f32_16x16x32_bf16 v[54:57], v[192:195], v[200:203], v[54:57]
	v_mfma_f32_16x16x32_bf16 v[46:49], v[184:187], v[220:223], v[46:49]
	v_mfma_f32_16x16x32_bf16 v[38:41], v[192:195], v[220:223], v[38:41]
	v_mfma_f32_16x16x32_bf16 v[30:33], v[184:187], v[228:231], v[30:33]
	v_mfma_f32_16x16x32_bf16 v[22:25], v[192:195], v[228:231], v[22:25]
	v_mfma_f32_16x16x32_bf16 v[14:17], v[184:187], v[236:239], v[14:17]
	v_mfma_f32_16x16x32_bf16 v[6:9], v[192:195], v[236:239], v[6:9]
	s_barrier
	s_setprio 0
	ds_read_b128 v[164:167], v158 offset:32768
	ds_read_b128 v[168:171], v158 offset:33792
	ds_read_b128 v[172:175], v158 offset:34816
	ds_read_b128 v[176:179], v158 offset:35840
	ds_read_b128 v[180:183], v158 offset:49152
	ds_read_b128 v[184:187], v158 offset:50176
	ds_read_b128 v[188:191], v158 offset:51200
	ds_read_b128 v[192:195], v158 offset:52224
	s_add_i32 s54, 0, 0x18000
	s_add_i32 s55, 0, 0x1c000
	s_add_u32 s22, s22, 0x80000
	s_addc_u32 s23, s23, 0
	s_mov_b32 m0, s44
	ds_read_b128 v[196:199], v162 offset:32768
	ds_read_b128 v[200:203], v162 offset:33792
	ds_read_b128 v[204:207], v162 offset:34816
	ds_read_b128 v[220:223], v162 offset:35840
	ds_read_b128 v[224:227], v162 offset:36864
	ds_read_b128 v[228:231], v162 offset:37888
	ds_read_b128 v[232:235], v162 offset:38912
	ds_read_b128 v[236:239], v162 offset:39936
	global_load_lds_dwordx4 v134, s[22:23]
	s_mov_b32 m0, s45
	s_nop 0
	global_load_lds_dwordx4 v132, s[22:23]
	s_waitcnt vmcnt(8)
	s_waitcnt lgkmcnt(0)
	s_setprio 1
	v_mfma_f32_16x16x32_bf16 v[122:125], v[164:167], v[196:199], v[122:125]
	v_mfma_f32_16x16x32_bf16 v[114:117], v[172:175], v[196:199], v[114:117]
	v_mfma_f32_16x16x32_bf16 v[106:109], v[164:167], v[204:207], v[106:109]
	v_mfma_f32_16x16x32_bf16 v[98:101], v[172:175], v[204:207], v[98:101]
	v_mfma_f32_16x16x32_bf16 v[90:93], v[164:167], v[224:227], v[90:93]
	v_mfma_f32_16x16x32_bf16 v[82:85], v[172:175], v[224:227], v[82:85]
	v_mfma_f32_16x16x32_bf16 v[74:77], v[164:167], v[232:235], v[74:77]
	v_mfma_f32_16x16x32_bf16 v[66:69], v[172:175], v[232:235], v[66:69]
	v_mfma_f32_16x16x32_bf16 v[122:125], v[168:171], v[200:203], v[122:125]
	v_mfma_f32_16x16x32_bf16 v[114:117], v[176:179], v[200:203], v[114:117]
	v_mfma_f32_16x16x32_bf16 v[106:109], v[168:171], v[220:223], v[106:109]
	v_mfma_f32_16x16x32_bf16 v[98:101], v[176:179], v[220:223], v[98:101]
	v_mfma_f32_16x16x32_bf16 v[90:93], v[168:171], v[228:231], v[90:93]
	v_mfma_f32_16x16x32_bf16 v[82:85], v[176:179], v[228:231], v[82:85]
	v_mfma_f32_16x16x32_bf16 v[74:77], v[168:171], v[236:239], v[74:77]
	v_mfma_f32_16x16x32_bf16 v[66:69], v[176:179], v[236:239], v[66:69]
	s_setprio 0
	s_setprio 1
	v_mfma_f32_16x16x32_bf16 v[126:129], v[180:183], v[196:199], v[126:129]
	v_mfma_f32_16x16x32_bf16 v[118:121], v[188:191], v[196:199], v[118:121]
	v_mfma_f32_16x16x32_bf16 v[110:113], v[180:183], v[204:207], v[110:113]
	v_mfma_f32_16x16x32_bf16 v[102:105], v[188:191], v[204:207], v[102:105]
	v_mfma_f32_16x16x32_bf16 v[94:97], v[180:183], v[224:227], v[94:97]
	v_mfma_f32_16x16x32_bf16 v[86:89], v[188:191], v[224:227], v[86:89]
	v_mfma_f32_16x16x32_bf16 v[78:81], v[180:183], v[232:235], v[78:81]
	v_mfma_f32_16x16x32_bf16 v[70:73], v[188:191], v[232:235], v[70:73]
	v_mfma_f32_16x16x32_bf16 v[126:129], v[184:187], v[200:203], v[126:129]
	v_mfma_f32_16x16x32_bf16 v[118:121], v[192:195], v[200:203], v[118:121]
	v_mfma_f32_16x16x32_bf16 v[110:113], v[184:187], v[220:223], v[110:113]
	v_mfma_f32_16x16x32_bf16 v[102:105], v[192:195], v[220:223], v[102:105]
	v_mfma_f32_16x16x32_bf16 v[94:97], v[184:187], v[228:231], v[94:97]
	v_mfma_f32_16x16x32_bf16 v[86:89], v[192:195], v[228:231], v[86:89]
	v_mfma_f32_16x16x32_bf16 v[78:81], v[184:187], v[236:239], v[78:81]
	v_mfma_f32_16x16x32_bf16 v[70:73], v[192:195], v[236:239], v[70:73]
	s_barrier
	s_setprio 0
	s_add_u32 vcc_lo, s22, 0xfff80080
	s_addc_u32 vcc_hi, s23, -1
	s_add_i32 s22, s54, s41
	s_add_i32 s56, s55, s41
	s_add_u32 s54, s20, 0x80
	s_addc_u32 s55, s21, 0
	s_add_u32 s20, s20, 0x80080
	s_addc_u32 s21, s21, 0
	s_mov_b32 m0, s22
	ds_read_b128 v[196:199], v162 offset:49152
	ds_read_b128 v[200:203], v162 offset:50176
	ds_read_b128 v[204:207], v162 offset:51200
	ds_read_b128 v[220:223], v162 offset:52224
	ds_read_b128 v[224:227], v162 offset:53248
	ds_read_b128 v[228:231], v162 offset:54272
	ds_read_b128 v[232:235], v162 offset:55296
	ds_read_b128 v[236:239], v162 offset:56320
	global_load_lds_dwordx4 v0, s[54:55]
	s_add_i32 m0, s22, 0x2000
	s_nop 0
	global_load_lds_dwordx4 v130, s[54:55]
	s_mov_b32 m0, s56
	s_nop 0
	global_load_lds_dwordx4 v0, s[20:21]
	s_add_i32 m0, s56, 0x2000
	s_nop 0
	global_load_lds_dwordx4 v130, s[20:21]
	s_mov_b32 m0, s46
	s_nop 0
	global_load_lds_dwordx4 v134, vcc
	s_mov_b32 m0, s47
	s_nop 0
	global_load_lds_dwordx4 v132, vcc
	s_waitcnt vmcnt(8)
	s_waitcnt lgkmcnt(0)
	s_setprio 1
	v_mfma_f32_16x16x32_bf16 v[58:61], v[164:167], v[196:199], v[58:61]
	v_mfma_f32_16x16x32_bf16 v[50:53], v[172:175], v[196:199], v[50:53]
	v_mfma_f32_16x16x32_bf16 v[42:45], v[164:167], v[204:207], v[42:45]
	v_mfma_f32_16x16x32_bf16 v[34:37], v[172:175], v[204:207], v[34:37]
	v_mfma_f32_16x16x32_bf16 v[26:29], v[164:167], v[224:227], v[26:29]
	v_mfma_f32_16x16x32_bf16 v[18:21], v[172:175], v[224:227], v[18:21]
	v_mfma_f32_16x16x32_bf16 v[10:13], v[164:167], v[232:235], v[10:13]
	v_mfma_f32_16x16x32_bf16 v[2:5], v[172:175], v[232:235], v[2:5]
	v_mfma_f32_16x16x32_bf16 v[58:61], v[168:171], v[200:203], v[58:61]
	v_mfma_f32_16x16x32_bf16 v[50:53], v[176:179], v[200:203], v[50:53]
	v_mfma_f32_16x16x32_bf16 v[42:45], v[168:171], v[220:223], v[42:45]
	v_mfma_f32_16x16x32_bf16 v[34:37], v[176:179], v[220:223], v[34:37]
	v_mfma_f32_16x16x32_bf16 v[26:29], v[168:171], v[228:231], v[26:29]
	v_mfma_f32_16x16x32_bf16 v[18:21], v[176:179], v[228:231], v[18:21]
	v_mfma_f32_16x16x32_bf16 v[10:13], v[168:171], v[236:239], v[10:13]
	v_mfma_f32_16x16x32_bf16 v[2:5], v[176:179], v[236:239], v[2:5]
	s_setprio 0
	s_setprio 1
	v_mfma_f32_16x16x32_bf16 v[62:65], v[180:183], v[196:199], v[62:65]
	v_mfma_f32_16x16x32_bf16 v[54:57], v[188:191], v[196:199], v[54:57]
	v_mfma_f32_16x16x32_bf16 v[46:49], v[180:183], v[204:207], v[46:49]
	v_mfma_f32_16x16x32_bf16 v[38:41], v[188:191], v[204:207], v[38:41]
	v_mfma_f32_16x16x32_bf16 v[30:33], v[180:183], v[224:227], v[30:33]
	v_mfma_f32_16x16x32_bf16 v[22:25], v[188:191], v[224:227], v[22:25]
	v_mfma_f32_16x16x32_bf16 v[14:17], v[180:183], v[232:235], v[14:17]
	v_mfma_f32_16x16x32_bf16 v[6:9], v[188:191], v[232:235], v[6:9]
	v_mfma_f32_16x16x32_bf16 v[62:65], v[184:187], v[200:203], v[62:65]
	v_mfma_f32_16x16x32_bf16 v[54:57], v[192:195], v[200:203], v[54:57]
	v_mfma_f32_16x16x32_bf16 v[46:49], v[184:187], v[220:223], v[46:49]
	v_mfma_f32_16x16x32_bf16 v[38:41], v[192:195], v[220:223], v[38:41]
	v_mfma_f32_16x16x32_bf16 v[30:33], v[184:187], v[228:231], v[30:33]
	v_mfma_f32_16x16x32_bf16 v[22:25], v[192:195], v[228:231], v[22:25]
	v_mfma_f32_16x16x32_bf16 v[14:17], v[184:187], v[236:239], v[14:17]
	v_mfma_f32_16x16x32_bf16 v[6:9], v[192:195], v[236:239], v[6:9]
	s_barrier
	s_setprio 0
	s_add_i32 s53, s53, 2
	s_add_u32 s18, s18, 0x100
	s_addc_u32 s19, s19, 0
	s_add_u32 s51, s51, 0x100
	s_addc_u32 s52, s52, 0
	s_cmp_gt_u32 s53, 29
	s_cbranch_scc0 .Lh1_4
.Ldone_4:
.Lpeel_done_4:
	s_and_b64 vcc, exec, s[4:5]
	s_cbranch_vccz .LBB0_1568

.LBB0_1571:
	s_and_b64 vcc, exec, s[4:5]
	s_cbranch_vccz .Lnoalign_4
.Lnoalign_4:
	s_waitcnt vmcnt(0)
	s_barrier
